# P2 score item loop: K-prefetch wait moved to the end of the item as vmcnt(16) (no longer drains the previous item's stores)
# speedup vs baseline: 1.0008x; 1.0002x over previous
; #define SCORE_LOADK(dst, b_, sub_) do { const bf16_t* kr_ = Z + ((size_t)(b_) * SEQ + 32 * (sub_) + r32) * NZ + ZC_IK + 8 * h; \
;         _Pragma("unroll") for (int s = 0; s < 4; ++s) dst[s] = *(const bf16x8*)(kr_ + 16 * s); } while (0)
; DI void score_range(const bf16_t* Z, float* SC, int i0, int i1, int lane) {
;     const int r32 = lane & 31, h = lane >> 5;
;     if (i0 >= i1) return;
;     int b = i0 / 2080; const int rem = i0 - b * 2080;
;     int qt = (int)((sqrtf(8.0f * (float)rem + 1.0f) - 1.0f) * 0.5f);
;     ...
;     while ((qt + 1) * (qt + 2) / 2 <= rem) ++qt;
;     int sub = rem - qt * (qt + 1) / 2;
;     bf16x8 qf[4][4]; float iwr[4][16]; float* sbase = nullptr; int Lrow = 0;
;     bf16x8 kf[4], kn[4];
;     ...
;     SCORE_LOADQ();
;     SCORE_LOADK(kf, b, sub);
.LBB0_410:
	s_add_i32 s4, s62, 2
	s_add_i32 s5, s62, 3
	s_mul_i32 s4, s4, s5
	s_lshr_b32 s5, s4, 31
	s_add_i32 s4, s4, s5
	s_add_i32 s62, s62, 1
	s_ashr_i32 s4, s4, 1
	s_cmp_le_i32 s4, s10
	s_cbranch_scc1 .LBB0_410
	s_add_i32 s11, s62, 1
	s_ashr_i32 s7, s6, 31
	s_mul_i32 s5, s6, 0x840000
	s_mul_hi_i32 s4, s6, 0x840000
	s_add_u32 s8, s44, s5
	s_addc_u32 s16, s45, s4
	s_lshl_b64 s[4:5], s[6:7], 11
	s_ashr_i32 s7, s62, 1
	s_add_i32 s17, s7, 1
	s_mul_i32 s7, s17, s7
	s_lshr_b32 s12, s7, 31
	s_add_i32 s7, s7, s12
	s_ashr_i32 s12, s7, 1
	s_ashr_i32 s13, s12, 31
	s_lshl_b64 s[12:13], s[12:13], 14
	s_add_u32 s12, s8, s12
	s_mul_i32 s11, s11, s62
	s_addc_u32 s13, s16, s13
	s_lshr_b32 s16, s11, 31
	s_add_i32 s11, s11, s16
	s_ashr_i32 s11, s11, 1
	s_sub_i32 s64, s10, s11
	s_lshl_b32 s7, s62, 5
	s_lshl_b32 s16, s64, 5
	s_lshl_b32 s8, s17, 6
	s_ashr_i32 s17, s16, 31
	s_ashr_i32 s10, s7, 31
	s_add_u32 s11, s4, s7
	s_mov_b32 s26, 0x8800
	v_mov_b32_e32 v1, 0x33000
	s_addc_u32 s10, s5, s10
	v_mad_u32_u24 v2, v133, s26, v1
	v_mov_b32_e32 v1, 0x35200
	s_mulk_i32 s10, 0x2200
	s_mul_hi_u32 s27, s11, 0x2200
	v_mad_u32_u24 v4, v133, s26, v1
	v_mov_b32_e32 v1, 0x37400
	s_add_i32 s27, s27, s10
	s_mulk_i32 s11, 0x2200
	v_mov_b32_e32 v141, 0
	v_mad_u32_u24 v6, v133, s26, v1
	v_mov_b32_e32 v1, 0x39600
	s_add_u32 s10, s22, s11
	v_mad_u32_u24 v8, v133, s26, v1
	v_mov_b32_e32 v9, v141
	s_addc_u32 s11, s23, s27
	v_lshl_add_u64 v[8:9], s[10:11], 0, v[8:9]
	s_movk_i32 s38, 0x1000
	v_mov_b32_e32 v7, v141
	v_add_co_u32_e32 v8, vcc, s38, v8
	v_lshl_add_u64 v[6:7], s[10:11], 0, v[6:7]
	s_nop 0
	v_addc_co_u32_e32 v9, vcc, 0, v9, vcc
	v_add_co_u32_e32 v6, vcc, s38, v6
	v_mov_b32_e32 v5, v141
	s_nop 0
	v_addc_co_u32_e32 v7, vcc, 0, v7, vcc
	v_lshl_add_u64 v[4:5], s[10:11], 0, v[4:5]
	v_mov_b32_e32 v3, v141
	global_load_dwordx2 v[8:9], v[8:9], off offset:432
	s_nop 0
	global_load_dwordx2 v[6:7], v[6:7], off offset:432
	v_add_co_u32_e32 v4, vcc, s38, v4
	v_lshl_add_u64 v[2:3], s[10:11], 0, v[2:3]
	s_nop 0
	v_addc_co_u32_e32 v5, vcc, 0, v5, vcc
	v_add_co_u32_e32 v2, vcc, s38, v2
	v_mov_b32_e32 v1, 0x4400
	s_nop 0
	v_addc_co_u32_e32 v3, vcc, 0, v3, vcc
	global_load_dwordx2 v[10:11], v[4:5], off offset:432
	global_load_dwordx2 v[12:13], v[2:3], off offset:432
	v_mad_u32_u24 v14, v133, s26, v1
	v_mov_b32_e32 v1, 0x26400
	v_mad_u32_u24 v2, v133, s26, v1
	v_mov_b32_e32 v1, 0x28600
	v_mad_u32_u24 v16, v133, s26, v1
	v_mov_b32_e32 v17, v141
	v_lshl_add_u64 v[16:17], s[10:11], 0, v[16:17]
	v_mov_b32_e32 v3, v141
	v_add_co_u32_e32 v16, vcc, s38, v16
	v_lshl_add_u64 v[2:3], s[10:11], 0, v[2:3]
	s_nop 0
	v_addc_co_u32_e32 v17, vcc, 0, v17, vcc
	v_add_co_u32_e32 v18, vcc, s38, v2
	v_and_or_b32 v34, s7, 32, v35
	s_nop 0
	v_addc_co_u32_e32 v19, vcc, 0, v3, vcc
	global_load_dwordx2 v[2:3], v[16:17], off offset:432
	s_nop 0
	global_load_dwordx2 v[16:17], v[18:19], off offset:432
	v_or_b32_e32 v32, s4, v134
	v_mov_b32_e32 v33, s5
	v_mad_i64_i32 v[36:37], s[4:5], v34, s8, 0
	v_lshl_add_u64 v[36:37], v[36:37], 2, s[12:13]
	s_movk_i32 s29, 0x2200
	v_lshl_add_u64 v[164:165], v[36:37], 0, v[140:141]
	v_lshl_add_u64 v[32:33], v[32:33], 0, s[16:17]
	v_mov_b64_e32 v[36:37], s[22:23]
	v_mad_u64_u32 v[36:37], s[4:5], v32, s29, v[36:37]
	v_mad_i32_i24 v37, v33, s29, v37
	v_lshlrev_b32_e32 v140, 1, v139
	v_mov_b32_e32 v1, 0x6600
	v_lshl_add_u64 v[32:33], v[36:37], 0, v[140:141]
	v_mad_u32_u24 v18, v133, s26, v1
	v_mov_b32_e32 v1, 0x11000
	global_load_dwordx4 v[116:119], v[32:33], off offset:3552
	global_load_dwordx4 v[120:123], v[32:33], off offset:3520
	global_load_dwordx4 v[124:127], v[32:33], off offset:3488
	global_load_dwordx4 v[128:131], v[32:33], off offset:3456
	s_mov_b32 s4, 0x3d800000
	v_mad_u32_u24 v20, v133, s26, v1
	v_mov_b32_e32 v1, 0x13200
	v_mad_u32_u24 v22, v133, s26, v1
	v_mov_b32_e32 v1, 0x15400
	v_mad_u32_u24 v24, v133, s26, v1
	v_mov_b32_e32 v1, 0x17600
	v_mad_u32_u24 v26, v133, s26, v1
	v_mov_b32_e32 v1, 0x22000
	v_mad_u32_u24 v28, v133, s26, v1
	v_mov_b32_e32 v1, 0x24200
	v_mad_u32_u24 v30, v133, s26, v1
	v_mov_b32_e32 v31, v141
	v_mov_b32_e32 v29, v141
	v_mov_b32_e32 v27, v141
	v_mov_b32_e32 v25, v141
	v_lshl_add_u64 v[24:25], s[10:11], 0, v[24:25]
	v_mov_b32_e32 v23, v141
	v_lshl_add_u64 v[22:23], s[10:11], 0, v[22:23]
	v_mov_b32_e32 v21, v141
	v_lshl_add_u64 v[20:21], s[10:11], 0, v[20:21]
	v_mov_b32_e32 v19, v141
	v_lshl_add_u64 v[18:19], s[10:11], 0, v[18:19]
	v_mov_b32_e32 v15, v141
	v_mov_b32_e32 v216, 0x2200
	v_lshl_add_u64 v[14:15], s[10:11], 0, v[14:15]
	v_mad_u32_u24 v4, v133, s26, v216
	v_mov_b32_e32 v5, v141
	v_lshl_add_u64 v[4:5], s[10:11], 0, v[4:5]
	v_mul_u32_u24_e32 v142, 0x8800, v133
	s_waitcnt vmcnt(9)
	v_and_b32_e32 v32, 0xffff0000, v9
	s_waitcnt vmcnt(8)
	v_and_b32_e32 v33, 0xffff0000, v7
	v_pk_mul_f32 v[162:163], v[32:33], s[4:5] op_sel_hi:[1,0]
	v_lshlrev_b32_e32 v33, 16, v7
	v_lshlrev_b32_e32 v32, 16, v9
	v_pk_mul_f32 v[160:161], v[32:33], s[4:5] op_sel_hi:[1,0]
	v_and_b32_e32 v33, 0xffff0000, v6
	v_lshlrev_b32_e32 v7, 16, v6
	v_lshlrev_b32_e32 v6, 16, v8
	v_pk_mul_f32 v[156:157], v[6:7], s[4:5] op_sel_hi:[1,0]
	v_and_b32_e32 v32, 0xffff0000, v8
	s_waitcnt vmcnt(7)
	v_and_b32_e32 v6, 0xffff0000, v11
	s_waitcnt vmcnt(6)
; #define SCORE_LOADK(dst, b_, sub_) do { const bf16_t* kr_ = Z + ((size_t)(b_) * SEQ + 32 * (sub_) + r32) * NZ + ZC_IK + 8 * h; \
;         _Pragma("unroll") for (int s = 0; s < 4; ++s) dst[s] = *(const bf16x8*)(kr_ + 16 * s); } while (0)
; DI void score_range(const bf16_t* Z, float* SC, int i0, int i1, int lane) {
;     ...
;     SCORE_LOADQ();
;     SCORE_LOADK(kf, b, sub);
	v_and_b32_e32 v7, 0xffff0000, v13
	v_pk_mul_f32 v[148:149], v[6:7], s[4:5] op_sel_hi:[1,0]
	v_lshlrev_b32_e32 v7, 16, v13
	v_lshlrev_b32_e32 v6, 16, v11
	v_pk_mul_f32 v[150:151], v[6:7], s[4:5] op_sel_hi:[1,0]
	v_and_b32_e32 v7, 0xffff0000, v12
	v_and_b32_e32 v6, 0xffff0000, v10
	v_pk_mul_f32 v[152:153], v[6:7], s[4:5] op_sel_hi:[1,0]
	v_lshlrev_b32_e32 v7, 16, v12
	v_lshlrev_b32_e32 v6, 16, v10
	v_pk_mul_f32 v[154:155], v[6:7], s[4:5] op_sel_hi:[1,0]
	v_lshl_add_u64 v[6:7], s[10:11], 0, v[30:31]
	v_add_co_u32_e32 v6, vcc, s38, v6
	v_lshl_add_u64 v[8:9], s[10:11], 0, v[28:29]
	s_nop 0
	v_addc_co_u32_e32 v7, vcc, 0, v7, vcc
	v_add_co_u32_e32 v8, vcc, s38, v8
	v_lshl_add_u64 v[12:13], s[10:11], 0, v[26:27]
	s_nop 0
	v_addc_co_u32_e32 v9, vcc, 0, v9, vcc
	v_add_co_u32_e32 v12, vcc, s38, v12
	global_load_dwordx2 v[6:7], v[6:7], off offset:432
	s_nop 0
	global_load_dwordx2 v[8:9], v[8:9], off offset:432
	v_addc_co_u32_e32 v13, vcc, 0, v13, vcc
	v_add_co_u32_e32 v24, vcc, s38, v24
	s_waitcnt vmcnt(6)
	v_and_b32_e32 v11, 0xffff0000, v17
	v_addc_co_u32_e32 v25, vcc, 0, v25, vcc
	v_add_co_u32_e32 v22, vcc, s38, v22
	v_and_b32_e32 v10, 0xffff0000, v3
	s_nop 0
	v_addc_co_u32_e32 v23, vcc, 0, v23, vcc
	v_add_co_u32_e32 v20, vcc, s38, v20
	v_pk_mul_f32 v[168:169], v[10:11], s[4:5] op_sel_hi:[1,0]
	s_nop 0
	v_addc_co_u32_e32 v21, vcc, 0, v21, vcc
	v_add_co_u32_e32 v18, vcc, s38, v18
	v_lshlrev_b32_e32 v11, 16, v17
	s_nop 0
	v_addc_co_u32_e32 v19, vcc, 0, v19, vcc
	v_add_co_u32_e32 v14, vcc, s38, v14
	v_lshlrev_b32_e32 v10, 16, v3
	s_nop 0
	v_addc_co_u32_e32 v15, vcc, 0, v15, vcc
	v_mov_b32_e32 v143, v141
	v_mul_u32_u24_e32 v1, 0x1100, v134
	v_add_co_u32_e32 v4, vcc, s38, v4
	v_pk_mul_f32 v[170:171], v[10:11], s[4:5] op_sel_hi:[1,0]
	v_and_b32_e32 v11, 0xffff0000, v16
	v_and_b32_e32 v10, 0xffff0000, v2
	global_load_dwordx2 v[12:13], v[12:13], off offset:432
	s_nop 0
	global_load_dwordx2 v[24:25], v[24:25], off offset:432
	v_addc_co_u32_e32 v5, vcc, 0, v5, vcc
	v_lshl_add_u64 v[26:27], s[10:11], 0, v[142:143]
	v_pk_mul_f32 v[172:173], v[10:11], s[4:5] op_sel_hi:[1,0]
	v_lshlrev_b32_e32 v10, 1, v1
	v_mov_b32_e32 v11, v141
	v_add_co_u32_e32 v26, vcc, s38, v26
	v_lshl_add_u64 v[10:11], s[10:11], 0, v[10:11]
	s_nop 0
	v_addc_co_u32_e32 v27, vcc, 0, v27, vcc
	v_lshl_add_u64 v[10:11], v[10:11], 0, v[140:141]
	global_load_dwordx2 v[22:23], v[22:23], off offset:432
	s_nop 0
	global_load_dwordx2 v[20:21], v[20:21], off offset:432
	s_nop 0
	global_load_dwordx2 v[18:19], v[18:19], off offset:432
	s_nop 0
	global_load_dwordx2 v[14:15], v[14:15], off offset:432
	s_nop 0
	global_load_dwordx2 v[4:5], v[4:5], off offset:432
	s_nop 0
	global_load_dwordx2 v[26:27], v[26:27], off offset:432
	s_nop 0
	global_load_dwordx4 v[84:87], v[10:11], off offset:3424
	global_load_dwordx4 v[88:91], v[10:11], off offset:3392
	global_load_dwordx4 v[92:95], v[10:11], off offset:3360
	global_load_dwordx4 v[96:99], v[10:11], off offset:3328
	global_load_dwordx4 v[100:103], v[10:11], off offset:3296
	global_load_dwordx4 v[104:107], v[10:11], off offset:3264
	global_load_dwordx4 v[108:111], v[10:11], off offset:3232
	global_load_dwordx4 v[112:115], v[10:11], off offset:3200
	global_load_dwordx4 v[52:55], v[10:11], off offset:3168
	global_load_dwordx4 v[56:59], v[10:11], off offset:3136
	global_load_dwordx4 v[60:63], v[10:11], off offset:3104
	global_load_dwordx4 v[64:67], v[10:11], off offset:3072
	global_load_dwordx4 v[68:71], v[10:11], off offset:3040
	global_load_dwordx4 v[72:75], v[10:11], off offset:3008
	global_load_dwordx4 v[76:79], v[10:11], off offset:2976
	global_load_dwordx4 v[80:83], v[10:11], off offset:2944
	v_lshlrev_b32_e32 v3, 16, v16
	v_lshlrev_b32_e32 v2, 16, v2
	v_pk_mul_f32 v[204:205], v[2:3], s[4:5] op_sel_hi:[1,0]
	v_mul_hi_u32_u24_e32 v145, 0x2200, v134
	v_mul_u32_u24_e32 v144, 0x2200, v134
	v_pk_mul_f32 v[158:159], v[32:33], s[4:5] op_sel_hi:[1,0]
	v_lshl_add_u64 v[146:147], s[22:23], 0, v[140:141]
	s_movk_i32 s39, 0x3000
	s_movk_i32 s46, 0x5000
	s_movk_i32 s47, 0x7000
	s_mov_b32 s50, 0x12000
	s_mov_b32 s51, 0x14000
	s_mov_b32 s52, 0x16000
	s_mov_b32 s53, 0x18000
	s_mov_b32 s54, 0x23000
	s_mov_b32 s55, 0x25000
	s_mov_b32 s56, 0x27000
	s_mov_b32 s57, 0x29000
	s_mov_b32 s58, 0x34000
	s_mov_b32 s59, 0x36000
	s_mov_b32 s60, 0x38000
	s_mov_b32 s61, 0x3a000
	s_waitcnt vmcnt(25)
	v_and_b32_e32 v2, 0xffff0000, v7
	s_waitcnt vmcnt(24)
	v_and_b32_e32 v3, 0xffff0000, v9
	v_pk_mul_f32 v[176:177], v[2:3], s[4:5] op_sel_hi:[1,0]
	v_lshlrev_b32_e32 v3, 16, v9
	v_lshlrev_b32_e32 v2, 16, v7
	v_pk_mul_f32 v[186:187], v[2:3], s[4:5] op_sel_hi:[1,0]
	v_and_b32_e32 v3, 0xffff0000, v8
	v_and_b32_e32 v2, 0xffff0000, v6
	v_pk_mul_f32 v[196:197], v[2:3], s[4:5] op_sel_hi:[1,0]
	v_lshlrev_b32_e32 v3, 16, v8
	v_lshlrev_b32_e32 v2, 16, v6
	v_pk_mul_f32 v[206:207], v[2:3], s[4:5] op_sel_hi:[1,0]
	s_waitcnt vmcnt(23)
	v_and_b32_e32 v2, 0xffff0000, v13
	s_waitcnt vmcnt(22)
	v_and_b32_e32 v3, 0xffff0000, v25
	v_pk_mul_f32 v[178:179], v[2:3], s[4:5] op_sel_hi:[1,0]
	v_lshlrev_b32_e32 v3, 16, v25
	v_lshlrev_b32_e32 v2, 16, v13
	v_pk_mul_f32 v[188:189], v[2:3], s[4:5] op_sel_hi:[1,0]
	v_and_b32_e32 v3, 0xffff0000, v24
	v_and_b32_e32 v2, 0xffff0000, v12
	v_pk_mul_f32 v[198:199], v[2:3], s[4:5] op_sel_hi:[1,0]
	v_lshlrev_b32_e32 v3, 16, v24
	v_lshlrev_b32_e32 v2, 16, v12
	v_pk_mul_f32 v[208:209], v[2:3], s[4:5] op_sel_hi:[1,0]
	s_waitcnt vmcnt(21)
	v_and_b32_e32 v2, 0xffff0000, v23
	s_waitcnt vmcnt(20)
	v_and_b32_e32 v3, 0xffff0000, v21
	v_pk_mul_f32 v[180:181], v[2:3], s[4:5] op_sel_hi:[1,0]
	v_lshlrev_b32_e32 v3, 16, v21
	v_lshlrev_b32_e32 v2, 16, v23
	v_pk_mul_f32 v[190:191], v[2:3], s[4:5] op_sel_hi:[1,0]
	v_and_b32_e32 v3, 0xffff0000, v20
	v_and_b32_e32 v2, 0xffff0000, v22
	v_pk_mul_f32 v[200:201], v[2:3], s[4:5] op_sel_hi:[1,0]
	v_lshlrev_b32_e32 v3, 16, v20
	v_lshlrev_b32_e32 v2, 16, v22
	v_pk_mul_f32 v[210:211], v[2:3], s[4:5] op_sel_hi:[1,0]
	s_waitcnt vmcnt(18)
	v_and_b32_e32 v3, 0xffff0000, v15
	v_and_b32_e32 v2, 0xffff0000, v19
	v_pk_mul_f32 v[182:183], v[2:3], s[4:5] op_sel_hi:[1,0]
	v_lshlrev_b32_e32 v3, 16, v15
	v_lshlrev_b32_e32 v2, 16, v19
	v_pk_mul_f32 v[192:193], v[2:3], s[4:5] op_sel_hi:[1,0]
	v_and_b32_e32 v3, 0xffff0000, v14
	v_and_b32_e32 v2, 0xffff0000, v18
	v_pk_mul_f32 v[202:203], v[2:3], s[4:5] op_sel_hi:[1,0]
	v_lshlrev_b32_e32 v3, 16, v14
	v_lshlrev_b32_e32 v2, 16, v18
	v_pk_mul_f32 v[212:213], v[2:3], s[4:5] op_sel_hi:[1,0]
	s_waitcnt vmcnt(16)
	v_and_b32_e32 v3, 0xffff0000, v27
	v_and_b32_e32 v2, 0xffff0000, v5
	v_pk_mul_f32 v[184:185], v[2:3], s[4:5] op_sel_hi:[1,0]
	v_lshlrev_b32_e32 v3, 16, v27
	v_lshlrev_b32_e32 v2, 16, v5
	v_pk_mul_f32 v[194:195], v[2:3], s[4:5] op_sel_hi:[1,0]
	v_and_b32_e32 v3, 0xffff0000, v26
	v_and_b32_e32 v2, 0xffff0000, v4
	v_pk_mul_f32 v[174:175], v[2:3], s[4:5] op_sel_hi:[1,0]
	v_lshlrev_b32_e32 v3, 16, v26
	v_lshlrev_b32_e32 v2, 16, v4
	v_pk_mul_f32 v[166:167], v[2:3], s[4:5] op_sel_hi:[1,0]
	s_add_i32 s5, s9, 1
	s_waitcnt vmcnt(0)
	s_branch .LBB0_414

; DI void score_range(const bf16_t* Z, float* SC, int i0, int i1, int lane) {
;     ...
;         if (more) {
;             const bool newq = (nq != qt) || (nb != b);
;             b = nb; qt = nq; sub = ns;
;             if (newq) SCORE_LOADQ();
; #pragma unroll
;             for (int s = 0; s < 4; ++s) kf[s] = kn[s];
;         }
.LBB0_413:
	s_waitcnt vmcnt(16)
	v_mov_b64_e32 v[118:119], v[38:39]
	v_mov_b64_e32 v[122:123], v[42:43]
	v_mov_b64_e32 v[126:127], v[46:47]
	v_mov_b64_e32 v[130:131], v[50:51]
	s_and_b64 vcc, exec, s[26:27]
	v_mov_b64_e32 v[116:117], v[36:37]
	v_mov_b64_e32 v[120:121], v[40:41]
	v_mov_b64_e32 v[124:125], v[44:45]
	v_mov_b64_e32 v[128:129], v[48:49]
	s_mov_b32 s62, s9
	s_mov_b32 s64, s63
	s_cbranch_vccnz .LBB0_419

; #define MFMA32(a, b, c) __builtin_amdgcn_mfma_f32_32x32x16_bf16((a), (b), (c), 0, 0, 0)
; DI void score_range(const bf16_t* Z, float* SC, int i0, int i1, int lane) {
;     ...
;         f32x16 sc = f16zero();
; #pragma unroll
;         for (int hh = 0; hh < 4; ++hh) {
;             f32x16 acc = f16zero();
; #pragma unroll
;             for (int s = 0; s < 4; ++s) acc = MFMA32(qf[hh][s], kf[s], acc);
; #pragma unroll
;             for (int r = 0; r < 16; ++r) sc[r] += iwr[hh][r] * fmaxf(acc[r], 0.f);
;         }
.LBB0_416:
	v_mfma_f32_32x32x16_bf16 v[10:25], v[80:83], v[128:131], 0
	s_lshl_b32 s66, s64, 5
	s_ashr_i32 s9, s8, 31
	s_ashr_i32 s67, s66, 31
	s_andn2_b64 vcc, exec, s[26:27]
	s_mov_b64 s[26:27], -1
	v_mfma_f32_32x32x16_bf16 v[10:25], v[76:79], v[124:127], v[10:25]
	v_mfma_f32_32x32x16_bf16 v[10:25], v[72:75], v[120:123], v[10:25]
	v_mfma_f32_32x32x16_bf16 v[10:25], v[68:71], v[116:119], v[10:25]
	s_nop 11
	v_max_f32_e32 v2, v11, v11
	v_max_f32_e32 v3, v12, v12
	v_max_f32_e32 v4, v13, v13
	v_max_f32_e32 v5, v14, v14
	v_max_f32_e32 v6, v15, v15
	v_max_f32_e32 v7, v16, v16
	v_max_f32_e32 v8, v17, v17
	v_max_f32_e32 v9, v18, v18
	v_max_f32_e32 v2, 0, v2
	v_max_f32_e32 v3, 0, v3
	v_max_f32_e32 v4, 0, v4
	v_max_f32_e32 v5, 0, v5
	v_max_f32_e32 v6, 0, v6
	v_max_f32_e32 v7, 0, v7
	v_max_f32_e32 v8, 0, v8
	v_max_f32_e32 v9, 0, v9
	v_max_f32_e32 v1, v10, v10
	v_fma_f32 v34, v166, v2, 0
	v_fma_f32 v137, v213, v3, 0
	v_fma_f32 v215, v212, v4, 0
	v_fma_f32 v217, v211, v5, 0
	v_fma_f32 v218, v210, v6, 0
	v_fma_f32 v219, v209, v7, 0
	v_fma_f32 v220, v208, v8, 0
	v_fma_f32 v221, v207, v9, 0
	v_mfma_f32_32x32x16_bf16 v[2:17], v[64:67], v[128:131], 0
	v_max_f32_e32 v18, v19, v19
	v_max_f32_e32 v18, 0, v18
	v_fma_f32 v222, v206, v18, 0
	v_max_f32_e32 v18, v20, v20
	v_max_f32_e32 v18, 0, v18
	v_fma_f32 v223, v205, v18, 0
	v_max_f32_e32 v18, v21, v21
	v_mfma_f32_32x32x16_bf16 v[2:17], v[60:63], v[124:127], v[2:17]
	v_max_f32_e32 v18, 0, v18
	v_fma_f32 v224, v204, v18, 0
	v_max_f32_e32 v18, v22, v22
	v_max_f32_e32 v18, 0, v18
	v_fma_f32 v225, v155, v18, 0
	v_max_f32_e32 v18, v23, v23
	v_max_f32_e32 v18, 0, v18
	v_mfma_f32_32x32x16_bf16 v[2:17], v[56:59], v[120:123], v[2:17]
	v_fma_f32 v226, v154, v18, 0
	v_max_f32_e32 v18, v24, v24
	v_max_f32_e32 v18, 0, v18
	v_fma_f32 v227, v157, v18, 0
	v_max_f32_e32 v18, v25, v25
	v_max_f32_e32 v18, 0, v18
	v_max_f32_e32 v1, 0, v1
	v_mfma_f32_32x32x16_bf16 v[2:17], v[52:55], v[116:119], v[2:17]
	v_fma_f32 v228, v156, v18, 0
	v_fma_f32 v1, v167, v1, 0
	v_mfma_f32_32x32x16_bf16 v[18:33], v[112:115], v[128:131], 0
	s_nop 8
	v_max_f32_e32 v2, v2, v2
	v_max_f32_e32 v2, 0, v2
	v_fmac_f32_e32 v1, v175, v2
	v_max_f32_e32 v2, v3, v3
	v_max_f32_e32 v2, 0, v2
	v_fmac_f32_e32 v34, v174, v2
	v_max_f32_e32 v2, v4, v4
	v_max_f32_e32 v2, 0, v2
	v_fmac_f32_e32 v137, v203, v2
	v_max_f32_e32 v2, v5, v5
	v_max_f32_e32 v2, 0, v2
	v_fmac_f32_e32 v215, v202, v2
	v_max_f32_e32 v2, v6, v6
	v_mfma_f32_32x32x16_bf16 v[18:33], v[108:111], v[124:127], v[18:33]
	v_max_f32_e32 v2, 0, v2
	v_fmac_f32_e32 v217, v201, v2
	v_max_f32_e32 v2, v7, v7
	v_max_f32_e32 v2, 0, v2
	v_fmac_f32_e32 v218, v200, v2
	v_max_f32_e32 v2, v8, v8
	v_max_f32_e32 v2, 0, v2
	v_fmac_f32_e32 v219, v199, v2
	v_max_f32_e32 v2, v9, v9
	v_max_f32_e32 v2, 0, v2
	v_fmac_f32_e32 v220, v198, v2
	v_max_f32_e32 v2, v10, v10
	v_mfma_f32_32x32x16_bf16 v[18:33], v[104:107], v[120:123], v[18:33]
	v_max_f32_e32 v2, 0, v2
	v_fmac_f32_e32 v221, v197, v2
	v_max_f32_e32 v2, v11, v11
	v_max_f32_e32 v2, 0, v2
	v_fmac_f32_e32 v222, v196, v2
	v_max_f32_e32 v2, v12, v12
	v_max_f32_e32 v2, 0, v2
	v_fmac_f32_e32 v223, v173, v2
	v_max_f32_e32 v2, v13, v13
	v_max_f32_e32 v2, 0, v2
	v_fmac_f32_e32 v224, v172, v2
	v_max_f32_e32 v2, v14, v14
	v_mfma_f32_32x32x16_bf16 v[18:33], v[100:103], v[116:119], v[18:33]
	v_max_f32_e32 v2, 0, v2
	v_fmac_f32_e32 v225, v153, v2
	v_max_f32_e32 v2, v15, v15
	v_max_f32_e32 v2, 0, v2
	v_fmac_f32_e32 v226, v152, v2
	v_max_f32_e32 v2, v16, v16
	v_max_f32_e32 v2, 0, v2
	v_fmac_f32_e32 v227, v159, v2
	v_max_f32_e32 v2, v17, v17
	v_max_f32_e32 v2, 0, v2
	v_fmac_f32_e32 v228, v158, v2
	s_nop 0
	v_max_f32_e32 v2, v18, v18
	v_max_f32_e32 v2, 0, v2
	v_fmac_f32_e32 v1, v195, v2
	v_max_f32_e32 v2, v19, v19
	v_max_f32_e32 v2, 0, v2
	v_fmac_f32_e32 v34, v194, v2
	v_max_f32_e32 v2, v20, v20
	v_max_f32_e32 v2, 0, v2
	v_fmac_f32_e32 v137, v193, v2
	v_max_f32_e32 v2, v21, v21
	v_max_f32_e32 v2, 0, v2
	v_fmac_f32_e32 v215, v192, v2
	v_max_f32_e32 v2, v22, v22
	v_max_f32_e32 v2, 0, v2
	v_fmac_f32_e32 v217, v191, v2
	v_max_f32_e32 v2, v23, v23
	v_max_f32_e32 v2, 0, v2
	v_fmac_f32_e32 v218, v190, v2
	v_max_f32_e32 v2, v24, v24
	v_max_f32_e32 v2, 0, v2
	v_fmac_f32_e32 v219, v189, v2
	v_max_f32_e32 v2, v25, v25
	v_max_f32_e32 v2, 0, v2
	v_fmac_f32_e32 v220, v188, v2
	v_max_f32_e32 v2, v26, v26
	v_max_f32_e32 v2, 0, v2
	v_fmac_f32_e32 v221, v187, v2
	v_mfma_f32_32x32x16_bf16 v[2:17], v[96:99], v[128:131], 0
	v_max_f32_e32 v18, v27, v27
	v_max_f32_e32 v18, 0, v18
	v_fmac_f32_e32 v222, v186, v18
	v_max_f32_e32 v18, v28, v28
	v_max_f32_e32 v18, 0, v18
	v_fmac_f32_e32 v223, v171, v18
	v_max_f32_e32 v18, v29, v29
	v_mfma_f32_32x32x16_bf16 v[2:17], v[92:95], v[124:127], v[2:17]
	v_max_f32_e32 v18, 0, v18
	v_fmac_f32_e32 v224, v170, v18
	v_max_f32_e32 v18, v30, v30
	v_max_f32_e32 v18, 0, v18
	v_fmac_f32_e32 v225, v151, v18
	v_max_f32_e32 v18, v31, v31
	v_max_f32_e32 v18, 0, v18
	v_mfma_f32_32x32x16_bf16 v[2:17], v[88:91], v[120:123], v[2:17]
	v_fmac_f32_e32 v226, v150, v18
	v_max_f32_e32 v18, v32, v32
	v_max_f32_e32 v18, 0, v18
	v_fmac_f32_e32 v227, v161, v18
	v_max_f32_e32 v18, v33, v33
	v_max_f32_e32 v18, 0, v18
	v_fmac_f32_e32 v228, v160, v18
	v_mfma_f32_32x32x16_bf16 v[2:17], v[84:87], v[116:119], v[2:17]
	s_nop 11
	v_max_f32_e32 v2, v2, v2
	v_max_f32_e32 v2, 0, v2
	v_fmac_f32_e32 v1, v185, v2
	v_max_f32_e32 v2, v3, v3
	v_max_f32_e32 v2, 0, v2
	v_fmac_f32_e32 v34, v184, v2
	v_max_f32_e32 v2, v4, v4
	v_max_f32_e32 v2, 0, v2
	v_fmac_f32_e32 v137, v183, v2
	v_max_f32_e32 v2, v5, v5
	v_max_f32_e32 v2, 0, v2
	v_fmac_f32_e32 v215, v182, v2
	v_max_f32_e32 v2, v6, v6
	v_max_f32_e32 v2, 0, v2
	v_fmac_f32_e32 v217, v181, v2
; DI void score_range(const bf16_t* Z, float* SC, int i0, int i1, int lane) {
;     ...
;             for (int r = 0; r < 16; ++r) sc[r] += iwr[hh][r] * fmaxf(acc[r], 0.f);
;         }
; #pragma unroll
;         for (int r = 0; r < 16; ++r) sbase[(size_t)((r & 3) + 8 * (r >> 2)) * Lrow + 32 * sub] = sc[r];
;         if (more) {
;             const bool newq = (nq != qt) || (nb != b);
;             b = nb; qt = nq; sub = ns;
;             if (newq) SCORE_LOADQ();
	v_max_f32_e32 v2, v7, v7
	v_max_f32_e32 v2, 0, v2
	v_fmac_f32_e32 v218, v180, v2
	v_max_f32_e32 v2, v8, v8
	v_max_f32_e32 v2, 0, v2
	v_fmac_f32_e32 v219, v179, v2
	v_max_f32_e32 v2, v9, v9
	v_max_f32_e32 v2, 0, v2
	v_fmac_f32_e32 v220, v178, v2
	v_max_f32_e32 v2, v10, v10
	v_max_f32_e32 v2, 0, v2
	v_fmac_f32_e32 v221, v177, v2
	v_max_f32_e32 v2, v11, v11
	v_max_f32_e32 v2, 0, v2
	v_fmac_f32_e32 v222, v176, v2
	v_max_f32_e32 v2, v12, v12
	v_max_f32_e32 v2, 0, v2
	v_fmac_f32_e32 v223, v169, v2
	v_max_f32_e32 v2, v13, v13
	v_max_f32_e32 v2, 0, v2
	v_fmac_f32_e32 v224, v168, v2
	v_max_f32_e32 v2, v14, v14
	v_max_f32_e32 v2, 0, v2
	v_fmac_f32_e32 v225, v149, v2
	v_max_f32_e32 v2, v15, v15
	v_max_f32_e32 v2, 0, v2
	v_fmac_f32_e32 v226, v148, v2
	v_max_f32_e32 v2, v16, v16
	v_max_f32_e32 v2, 0, v2
	v_fmac_f32_e32 v227, v163, v2
	v_max_f32_e32 v2, v17, v17
	v_max_f32_e32 v2, 0, v2
	v_fmac_f32_e32 v228, v162, v2
	v_lshl_add_u64 v[2:3], s[66:67], 2, v[164:165]
	s_lshl_b64 s[66:67], s[8:9], 2
	global_store_dword v[2:3], v1, off
	v_lshl_add_u64 v[2:3], v[2:3], 0, s[66:67]
	global_store_dword v[2:3], v34, off
	v_lshl_add_u64 v[2:3], v[2:3], 0, s[66:67]
	global_store_dword v[2:3], v137, off
	v_lshl_add_u64 v[2:3], v[2:3], 0, s[66:67]
	global_store_dword v[2:3], v215, off
	v_mad_i64_i32 v[2:3], s[68:69], s8, 20, v[2:3]
	global_store_dword v[2:3], v217, off
	v_lshl_add_u64 v[2:3], v[2:3], 0, s[66:67]
	global_store_dword v[2:3], v218, off
	v_lshl_add_u64 v[2:3], v[2:3], 0, s[66:67]
	global_store_dword v[2:3], v219, off
	v_lshl_add_u64 v[2:3], v[2:3], 0, s[66:67]
	global_store_dword v[2:3], v220, off
	v_mad_i64_i32 v[2:3], s[68:69], s8, 20, v[2:3]
	global_store_dword v[2:3], v221, off
	v_lshl_add_u64 v[2:3], v[2:3], 0, s[66:67]
	global_store_dword v[2:3], v222, off
	v_lshl_add_u64 v[2:3], v[2:3], 0, s[66:67]
	global_store_dword v[2:3], v223, off
	v_lshl_add_u64 v[2:3], v[2:3], 0, s[66:67]
	global_store_dword v[2:3], v224, off
	v_mad_i64_i32 v[2:3], s[68:69], s8, 20, v[2:3]
	global_store_dword v[2:3], v225, off
	v_lshl_add_u64 v[2:3], v[2:3], 0, s[66:67]
	global_store_dword v[2:3], v226, off
	v_lshl_add_u64 v[2:3], v[2:3], 0, s[66:67]
	global_store_dword v[2:3], v227, off
	v_lshl_add_u64 v[2:3], v[2:3], 0, s[66:67]
	global_store_dword v[2:3], v228, off
	s_cbranch_vccnz .LBB0_413
	s_and_b64 s[12:13], s[12:13], exec
	s_cselect_b32 s7, 0, s65
	s_and_b64 s[12:13], s[16:17], exec
	s_cselect_b32 s9, s7, s62
	s_cmp_lg_u32 s9, s62
	s_cselect_b64 s[12:13], -1, 0
	s_or_b64 s[10:11], s[12:13], s[10:11]
	s_andn2_b64 vcc, exec, s[10:11]
	s_cbranch_vccnz .LBB0_412
	s_ashr_i32 s7, s6, 31
	s_lshl_b64 s[10:11], s[6:7], 11
	s_lshl_b32 s7, s9, 5
	s_ashr_i32 s8, s7, 31
	s_add_u32 s10, s10, s7
	s_addc_u32 s8, s11, s8
	s_mulk_i32 s8, 0x2200
	s_mul_hi_u32 s11, s10, 0x2200
	s_add_i32 s11, s11, s8
	s_mulk_i32 s10, 0x2200
	s_add_u32 s10, s22, s10
	s_addc_u32 s11, s23, s11
	v_lshl_add_u64 v[2:3], s[10:11], 0, v[142:143]
	v_add_co_u32_e32 v4, vcc, s38, v2
	v_lshl_add_u64 v[8:9], s[10:11], 0, v[144:145]
	s_nop 0
	v_addc_co_u32_e32 v5, vcc, 0, v3, vcc
	v_add_co_u32_e32 v6, vcc, s39, v2
	v_lshl_add_u64 v[8:9], v[8:9], 0, v[140:141]
	s_nop 0
	v_addc_co_u32_e32 v7, vcc, 0, v3, vcc
	global_load_dwordx2 v[4:5], v[4:5], off offset:432
	s_nop 0
	global_load_dwordx2 v[6:7], v[6:7], off offset:944
	v_add_co_u32_e32 v10, vcc, s46, v2
	s_ashr_i32 s10, s9, 1
	s_nop 0
	v_addc_co_u32_e32 v11, vcc, 0, v3, vcc
	v_add_co_u32_e32 v12, vcc, s47, v2
	s_add_i32 s11, s10, 1
	s_nop 0
	v_addc_co_u32_e32 v13, vcc, 0, v3, vcc
	v_add_co_u32_e32 v14, vcc, s50, v2
	global_load_dwordx2 v[10:11], v[10:11], off offset:1456
	s_nop 0
	global_load_dwordx2 v[12:13], v[12:13], off offset:1968
	v_addc_co_u32_e32 v15, vcc, 0, v3, vcc
	v_add_co_u32_e32 v16, vcc, s51, v2
	s_lshl_b32 s8, s11, 6
	s_nop 0
	v_addc_co_u32_e32 v17, vcc, 0, v3, vcc
	v_add_co_u32_e32 v18, vcc, s52, v2
	global_load_dwordx2 v[14:15], v[14:15], off offset:432
	s_nop 0
	global_load_dwordx2 v[16:17], v[16:17], off offset:944
	v_addc_co_u32_e32 v19, vcc, 0, v3, vcc
	v_add_co_u32_e32 v20, vcc, s53, v2
	s_mul_i32 s13, s6, 0x840000
	s_nop 0
	v_addc_co_u32_e32 v21, vcc, 0, v3, vcc
	v_add_co_u32_e32 v22, vcc, s54, v2
	global_load_dwordx2 v[18:19], v[18:19], off offset:1456
	s_nop 0
	global_load_dwordx2 v[20:21], v[20:21], off offset:1968
	v_addc_co_u32_e32 v23, vcc, 0, v3, vcc
	v_add_co_u32_e32 v24, vcc, s55, v2
	s_mul_hi_i32 s12, s6, 0x840000
	s_nop 0
	v_addc_co_u32_e32 v25, vcc, 0, v3, vcc
	v_add_co_u32_e32 v26, vcc, s56, v2
	global_load_dwordx4 v[80:83], v[8:9], off offset:2944
	global_load_dwordx4 v[76:79], v[8:9], off offset:2976
	global_load_dwordx4 v[72:75], v[8:9], off offset:3008
	global_load_dwordx4 v[68:71], v[8:9], off offset:3040
	global_load_dwordx4 v[64:67], v[8:9], off offset:3072
	global_load_dwordx4 v[60:63], v[8:9], off offset:3104
	global_load_dwordx4 v[56:59], v[8:9], off offset:3136
	global_load_dwordx4 v[52:55], v[8:9], off offset:3168
	s_nop 0
	global_load_dwordx2 v[22:23], v[22:23], off offset:432
	s_nop 0
	global_load_dwordx2 v[24:25], v[24:25], off offset:944
	s_nop 0
	global_load_dwordx4 v[112:115], v[8:9], off offset:3200
	global_load_dwordx4 v[108:111], v[8:9], off offset:3232
	global_load_dwordx4 v[104:107], v[8:9], off offset:3264
	global_load_dwordx4 v[100:103], v[8:9], off offset:3296
	global_load_dwordx4 v[96:99], v[8:9], off offset:3328
	global_load_dwordx4 v[92:95], v[8:9], off offset:3360
	global_load_dwordx4 v[88:91], v[8:9], off offset:3392
	global_load_dwordx4 v[84:87], v[8:9], off offset:3424
	v_addc_co_u32_e32 v27, vcc, 0, v3, vcc
	v_add_co_u32_e32 v28, vcc, s57, v2
	s_add_u32 s13, s44, s13
	s_nop 0
	v_addc_co_u32_e32 v29, vcc, 0, v3, vcc
	global_load_dwordx2 v[26:27], v[26:27], off offset:1456
	s_nop 0
	global_load_dwordx2 v[28:29], v[28:29], off offset:1968
	v_add_co_u32_e32 v30, vcc, s58, v2
	s_mul_i32 s10, s11, s10
	s_nop 0
	v_addc_co_u32_e32 v31, vcc, 0, v3, vcc
	v_add_co_u32_e32 v32, vcc, s59, v2
	s_addc_u32 s12, s45, s12
	s_nop 0
	v_addc_co_u32_e32 v33, vcc, 0, v3, vcc
	global_load_dwordx2 v[30:31], v[30:31], off offset:432
	s_nop 0
	global_load_dwordx2 v[32:33], v[32:33], off offset:944
	s_lshr_b32 s11, s10, 31
	s_add_i32 s10, s10, s11
	s_ashr_i32 s10, s10, 1
	s_ashr_i32 s11, s10, 31
	s_lshl_b64 s[10:11], s[10:11], 14
	s_add_u32 s10, s13, s10
	v_and_or_b32 v1, s7, 32, v35
	s_addc_u32 s11, s12, s11
	s_waitcnt vmcnt(29)
	v_lshlrev_b32_e32 v9, 16, v4
	s_waitcnt vmcnt(28)
	v_lshlrev_b32_e32 v8, 16, v6
	v_pk_mul_f32 v[166:167], v[8:9], s[4:5] op_sel_hi:[1,0]
	v_and_b32_e32 v9, 0xffff0000, v4
	v_and_b32_e32 v8, 0xffff0000, v6
	v_pk_mul_f32 v[174:175], v[8:9], s[4:5] op_sel_hi:[1,0]
	v_add_co_u32_e32 v8, vcc, s60, v2
	v_lshlrev_b32_e32 v117, 16, v5
	s_nop 0
	v_addc_co_u32_e32 v9, vcc, 0, v3, vcc
	v_add_co_u32_e32 v2, vcc, s61, v2
	v_and_b32_e32 v5, 0xffff0000, v5
	s_nop 0
	v_addc_co_u32_e32 v3, vcc, 0, v3, vcc
	global_load_dwordx2 v[8:9], v[8:9], off offset:1456
	s_nop 0
	global_load_dwordx2 v[2:3], v[2:3], off offset:1968
	v_and_b32_e32 v4, 0xffff0000, v7
	v_pk_mul_f32 v[184:185], v[4:5], s[4:5] op_sel_hi:[1,0]
	s_waitcnt vmcnt(29)
	v_lshlrev_b32_e32 v5, 16, v10
	s_waitcnt vmcnt(28)
	v_lshlrev_b32_e32 v4, 16, v12
	v_pk_mul_f32 v[212:213], v[4:5], s[4:5] op_sel_hi:[1,0]
	v_and_b32_e32 v5, 0xffff0000, v10
	v_and_b32_e32 v4, 0xffff0000, v12
	v_pk_mul_f32 v[202:203], v[4:5], s[4:5] op_sel_hi:[1,0]
	v_lshlrev_b32_e32 v5, 16, v11
	v_lshlrev_b32_e32 v4, 16, v13
	v_pk_mul_f32 v[192:193], v[4:5], s[4:5] op_sel_hi:[1,0]
	v_and_b32_e32 v5, 0xffff0000, v11
	v_and_b32_e32 v4, 0xffff0000, v13
	v_pk_mul_f32 v[182:183], v[4:5], s[4:5] op_sel_hi:[1,0]
	s_waitcnt vmcnt(27)
	v_lshlrev_b32_e32 v5, 16, v14
	s_waitcnt vmcnt(26)
	v_lshlrev_b32_e32 v4, 16, v16
	v_pk_mul_f32 v[210:211], v[4:5], s[4:5] op_sel_hi:[1,0]
	v_and_b32_e32 v5, 0xffff0000, v14
	v_and_b32_e32 v4, 0xffff0000, v16
	v_pk_mul_f32 v[200:201], v[4:5], s[4:5] op_sel_hi:[1,0]
	v_lshlrev_b32_e32 v5, 16, v15
	v_lshlrev_b32_e32 v4, 16, v17
	v_pk_mul_f32 v[190:191], v[4:5], s[4:5] op_sel_hi:[1,0]
	v_and_b32_e32 v5, 0xffff0000, v15
	v_and_b32_e32 v4, 0xffff0000, v17
	v_pk_mul_f32 v[180:181], v[4:5], s[4:5] op_sel_hi:[1,0]
	s_waitcnt vmcnt(25)
	v_lshlrev_b32_e32 v5, 16, v18
	s_waitcnt vmcnt(24)
	v_lshlrev_b32_e32 v4, 16, v20
	v_pk_mul_f32 v[208:209], v[4:5], s[4:5] op_sel_hi:[1,0]
	v_and_b32_e32 v5, 0xffff0000, v18
	v_and_b32_e32 v4, 0xffff0000, v20
	v_pk_mul_f32 v[198:199], v[4:5], s[4:5] op_sel_hi:[1,0]
	v_lshlrev_b32_e32 v5, 16, v19
	v_lshlrev_b32_e32 v4, 16, v21
	v_pk_mul_f32 v[188:189], v[4:5], s[4:5] op_sel_hi:[1,0]
	v_and_b32_e32 v5, 0xffff0000, v19
	v_and_b32_e32 v4, 0xffff0000, v21
	v_pk_mul_f32 v[178:179], v[4:5], s[4:5] op_sel_hi:[1,0]
	s_waitcnt vmcnt(15)
	v_lshlrev_b32_e32 v5, 16, v22
	s_waitcnt vmcnt(14)
	v_lshlrev_b32_e32 v4, 16, v24
	v_pk_mul_f32 v[206:207], v[4:5], s[4:5] op_sel_hi:[1,0]
	v_and_b32_e32 v5, 0xffff0000, v22
	v_and_b32_e32 v4, 0xffff0000, v24
	v_pk_mul_f32 v[196:197], v[4:5], s[4:5] op_sel_hi:[1,0]
	v_lshlrev_b32_e32 v5, 16, v23
	v_lshlrev_b32_e32 v4, 16, v25
	v_pk_mul_f32 v[186:187], v[4:5], s[4:5] op_sel_hi:[1,0]
	v_and_b32_e32 v5, 0xffff0000, v23
	v_and_b32_e32 v4, 0xffff0000, v25
	v_pk_mul_f32 v[176:177], v[4:5], s[4:5] op_sel_hi:[1,0]
	s_waitcnt vmcnt(5)
	v_lshlrev_b32_e32 v5, 16, v26
	s_waitcnt vmcnt(4)
	v_lshlrev_b32_e32 v4, 16, v28
	v_pk_mul_f32 v[204:205], v[4:5], s[4:5] op_sel_hi:[1,0]
	v_and_b32_e32 v5, 0xffff0000, v26
	v_and_b32_e32 v4, 0xffff0000, v28
	v_pk_mul_f32 v[172:173], v[4:5], s[4:5] op_sel_hi:[1,0]
	v_lshlrev_b32_e32 v5, 16, v27
	v_lshlrev_b32_e32 v4, 16, v29
	v_pk_mul_f32 v[170:171], v[4:5], s[4:5] op_sel_hi:[1,0]
	v_and_b32_e32 v5, 0xffff0000, v27
	v_and_b32_e32 v4, 0xffff0000, v29
	v_pk_mul_f32 v[168:169], v[4:5], s[4:5] op_sel_hi:[1,0]
	s_waitcnt vmcnt(3)
	v_lshlrev_b32_e32 v5, 16, v30
	s_waitcnt vmcnt(2)
	v_lshlrev_b32_e32 v4, 16, v32
	v_pk_mul_f32 v[154:155], v[4:5], s[4:5] op_sel_hi:[1,0]
	v_and_b32_e32 v5, 0xffff0000, v30
	v_and_b32_e32 v4, 0xffff0000, v32
	v_pk_mul_f32 v[152:153], v[4:5], s[4:5] op_sel_hi:[1,0]
	v_lshlrev_b32_e32 v5, 16, v31
	v_lshlrev_b32_e32 v4, 16, v33
	v_pk_mul_f32 v[150:151], v[4:5], s[4:5] op_sel_hi:[1,0]
	v_and_b32_e32 v5, 0xffff0000, v31
	v_and_b32_e32 v4, 0xffff0000, v33
	v_pk_mul_f32 v[148:149], v[4:5], s[4:5] op_sel_hi:[1,0]
	v_lshlrev_b32_e32 v116, 16, v7
	v_pk_mul_f32 v[194:195], v[116:117], s[4:5] op_sel_hi:[1,0]
	s_waitcnt vmcnt(1)
	v_lshlrev_b32_e32 v5, 16, v8
	s_waitcnt vmcnt(0)
	v_lshlrev_b32_e32 v4, 16, v2
	v_pk_mul_f32 v[156:157], v[4:5], s[4:5] op_sel_hi:[1,0]
	v_and_b32_e32 v5, 0xffff0000, v8
	v_and_b32_e32 v4, 0xffff0000, v2
	v_pk_mul_f32 v[158:159], v[4:5], s[4:5] op_sel_hi:[1,0]
	v_lshlrev_b32_e32 v5, 16, v9
	v_lshlrev_b32_e32 v4, 16, v3
	v_pk_mul_f32 v[160:161], v[4:5], s[4:5] op_sel_hi:[1,0]
	v_and_b32_e32 v5, 0xffff0000, v9
	v_and_b32_e32 v4, 0xffff0000, v3
	v_mad_i64_i32 v[2:3], s[12:13], v1, s8, 0
	v_pk_mul_f32 v[162:163], v[4:5], s[4:5] op_sel_hi:[1,0]
	v_lshl_add_u64 v[2:3], v[2:3], 2, s[10:11]
	v_lshlrev_b32_e32 v4, 2, v134
	v_mov_b32_e32 v5, v141
	v_lshl_add_u64 v[164:165], v[2:3], 0, v[4:5]
	s_branch .LBB0_412
